# dilated attention: all four table quads of a half-tile read up front into spare registers (no mid-softmax LDS round trips)
# speedup vs baseline: 1.0062x; 1.0038x over previous
; #define LAS __attribute__((address_space(3)))
; __device__ __forceinline__ float fast_exp2(float x) { return __builtin_amdgcn_exp2f(x); }
; __device__ __forceinline__ float xmax(float a) { auto rr = __builtin_amdgcn_permlane32_swap(__float_as_uint(a), __float_as_uint(a), false, false); return fmaxf(__uint_as_float(rr[0]), __uint_as_float(rr[1])); }
; #define AT_KLOAD(bufbase, hf) do { _Pragma("unroll") for (int j_ = 0; j_ < NK; ++j_) kf[j_] = *(const LAS bf16x8*)((bufbase) + (2 * j_ + hi) * 1024 + (hf) * 512 + r32 * 16); } while (0)
; template <int MODE, int NQ>
; __device__ __forceinline__ void attn_unit(LAS unsigned char* lds, const Params& P, int layer, int b, int h, int qb) {
;     ...
;                 for (int d0 = 0; d0 < ND0; ++d0) sc[cc] = __builtin_amdgcn_mfma_f32_32x32x16_bf16(kf[(cc % NMAP) * ND0 + d0], qf[cc][d0], sc[cc], 0, 0, 0);
;             }
;             __builtin_amdgcn_sched_barrier(0);
;             AT_VLOAD(cur, hf);
;             if (hf == 0) AT_KLOAD(cur, 1); else if (it + 1 < NT) AT_KLOAD(nxt, 0);
;             __builtin_amdgcn_sched_barrier(0);
;             bf16x8 pw[NC][2]; float rmrel[NC]; bool alive = false;
; #pragma unroll
;             for (int cc = 0; cc < NC; ++cc) {
;                 f32x16& s0 = sc[cc];
;                 float mn;
;                 if (MODE != 0) {
;                     const LAS f32x4* tp4 = (const LAS f32x4*)(tlane + (kt * 64 + hf * 32) * 4);
;                     float rm = -3e38f;
; #pragma unroll
;                     for (int g = 0; g < 4; ++g) { const f32x4 t4 = tp4[2 * g];
; #pragma unroll
;                         for (int i = 0; i < 4; ++i) { s0[4 * g + i] = s0[4 * g + i] * c + t4[i]; rm = fmaxf(rm, s0[4 * g + i]); } }
;                     rm = xmax(rm);
;                     mn = fmaxf(mrun[cc], rm);
;                     rmrel[cc] = rm;
;                 } else {
;                     float rm = -3e38f;
; #pragma unroll
;                     for (int r = 0; r < 16; ++r) rm = fmaxf(rm, s0[r]);
;                     rm = xmax(rm);
;                     mn = fmaxf(mrun[cc], rm * c);
;                 }
;                 if (__any(mn > mrun[cc] + AT_THR)) {
;                     const float al = fast_exp2(mrun[cc] - mn); lrun[cc] *= al;
; #pragma unroll
;                     for (int r = 0; r < 16; ++r) { o[cc][0][r] *= al; o[cc][1][r] *= al; }
;                     mrun[cc] = mn;
;                 }
.LBB0_505:
	s_add_i32 s16, s16, -2
	s_cmp_ge_i32 s16, s6
	s_mul_i32 s17, s19, 0x5000
	s_cselect_b32 s16, s6, 0
	s_add_i32 s17, s17, 0
	v_add3_u32 v0, s17, v130, v131
	s_lshl_b32 s20, s16, 8
	s_waitcnt lgkmcnt(3)
	v_mfma_f32_32x32x16_bf16 v[48:63], v[96:99], v[64:67], 0
	v_add_u32_e32 v15, v0, v124
	ds_read_b64_tr_b16 v[2:3], v15 offset:12288
	ds_read_b64_tr_b16 v[4:5], v15 offset:12800
	ds_read_b64_tr_b16 v[6:7], v15 offset:13312
	ds_read_b64_tr_b16 v[8:9], v15 offset:13824
	ds_read_b64_tr_b16 v[10:11], v15 offset:16384
	ds_read_b64_tr_b16 v[12:13], v15 offset:16896
	ds_read_b64_tr_b16 v[104:105], v15 offset:17408
	ds_read_b64_tr_b16 v[106:107], v15 offset:17920
	v_add3_u32 v0, s17, v126, v127
	s_waitcnt lgkmcnt(10)
	v_mfma_f32_32x32x16_bf16 v[48:63], v[100:103], v[68:71], v[48:63]
	ds_read_b128 v[96:99], v0 offset:512
	ds_read_b128 v[100:103], v0 offset:2560
	s_waitcnt lgkmcnt(11)
	v_mfma_f32_32x32x16_bf16 v[48:63], v[92:95], v[72:75], v[48:63]
	s_waitcnt lgkmcnt(10)
	v_mfma_f32_32x32x16_bf16 v[48:63], v[88:91], v[76:79], v[48:63]
	ds_read_b128 v[92:95], v0 offset:4608
	ds_read_b128 v[88:91], v0 offset:6656
	v_subrev_u32_e32 v0, s20, v133
	ds_read_b128 v[112:115], v0
	ds_read_b128 v[108:111], v0 offset:32
	ds_read_b128 v[144:147], v0 offset:64
	ds_read_b128 v[148:151], v0 offset:96
	s_waitcnt lgkmcnt(3)
	s_nop 5
	v_fmamk_f32 v135, v48, 0x3e38aa3b, v112
	v_fmamk_f32 v14, v49, 0x3e38aa3b, v113
	v_fmamk_f32 v112, v50, 0x3e38aa3b, v114
	v_fmac_f32_e32 v115, 0x3e38aa3b, v51
	v_max3_f32 v48, v135, s68, v14
	v_max3_f32 v48, v48, v112, v115
	s_waitcnt lgkmcnt(2)
	v_fmamk_f32 v113, v52, 0x3e38aa3b, v108
	v_fmamk_f32 v108, v53, 0x3e38aa3b, v109
	v_max3_f32 v52, v48, v113, v108
	v_fmamk_f32 v109, v54, 0x3e38aa3b, v110
	v_fmac_f32_e32 v111, 0x3e38aa3b, v55
	v_max3_f32 v114, v52, v109, v111
	s_waitcnt lgkmcnt(1)
	v_fmamk_f32 v110, v56, 0x3e38aa3b, v144
	v_fmamk_f32 v56, v57, 0x3e38aa3b, v145
	v_max3_f32 v0, v114, v110, v56
	v_fmamk_f32 v57, v58, 0x3e38aa3b, v146
	v_fmac_f32_e32 v147, 0x3e38aa3b, v59
	v_max3_f32 v0, v0, v57, v147
	s_waitcnt lgkmcnt(0)
	v_fmamk_f32 v50, v60, 0x3e38aa3b, v148
	v_fmamk_f32 v48, v61, 0x3e38aa3b, v149
	v_max3_f32 v0, v0, v50, v48
	v_fmamk_f32 v49, v62, 0x3e38aa3b, v150
	v_fmac_f32_e32 v151, 0x3e38aa3b, v63
	v_max3_f32 v0, v0, v49, v151
	v_mov_b32_e32 v52, v0
	s_nop 1
	v_permlane32_swap_b32_e32 v0, v52
	v_max_f32_e32 v52, v0, v52
	v_max_f32_e32 v0, v134, v52
	v_add_f32_e32 v53, 0x41000000, v134
	v_cmp_gt_f32_e32 vcc, v0, v53
	s_cbranch_vccz .LBB0_507
	v_sub_f32_e32 v53, v134, v0
	s_mov_b32 s61, 0
	v_exp_f32_e32 v54, v53
	s_nop 0
	v_pk_mul_f32 v[46:47], v[46:47], v[54:55] op_sel_hi:[1,0]
	v_pk_mul_f32 v[44:45], v[44:45], v[54:55] op_sel_hi:[1,0]
	v_pk_mul_f32 v[42:43], v[42:43], v[54:55] op_sel_hi:[1,0]
	v_pk_mul_f32 v[40:41], v[40:41], v[54:55] op_sel_hi:[1,0]
	v_pk_mul_f32 v[38:39], v[38:39], v[54:55] op_sel_hi:[1,0]
	v_pk_mul_f32 v[36:37], v[36:37], v[54:55] op_sel_hi:[1,0]
	v_pk_mul_f32 v[34:35], v[34:35], v[54:55] op_sel_hi:[1,0]
	v_pk_mul_f32 v[32:33], v[32:33], v[54:55] op_sel_hi:[1,0]
	v_pk_mul_f32 v[30:31], v[30:31], v[54:55] op_sel_hi:[1,0]
	v_pk_mul_f32 v[28:29], v[28:29], v[54:55] op_sel_hi:[1,0]
	v_pk_mul_f32 v[26:27], v[26:27], v[54:55] op_sel_hi:[1,0]
	v_pk_mul_f32 v[24:25], v[24:25], v[54:55] op_sel_hi:[1,0]
	v_pk_mul_f32 v[22:23], v[22:23], v[54:55] op_sel_hi:[1,0]
	v_pk_mul_f32 v[20:21], v[20:21], v[54:55] op_sel_hi:[1,0]
	v_pk_mul_f32 v[18:19], v[18:19], v[54:55] op_sel_hi:[1,0]
	v_pk_mul_f32 v[16:17], v[16:17], v[54:55] op_sel_hi:[1,0]
	v_mul_f32_e32 v132, v132, v54
	s_branch .LBB0_508

; __device__ __forceinline__ float fast_exp2(float x) { return __builtin_amdgcn_exp2f(x); }
; template <int MODE, int NQ>
; __device__ __forceinline__ void attn_unit(LAS unsigned char* lds, const Params& P, int layer, int b, int h, int qb) {
;     ...
;                 mn = mrun[cc];
;                 if (MODE != 0) rmrel[cc] -= mn;
;                 const bool dead = (MODE != 0) && __all(rmrel[cc] < -136.f);
;                 if (dead) { pw[cc][0] = zero8; pw[cc][1] = zero8; }
;                 else {
;                     alive = true;
;                     if (MODE != 0) {
; #pragma unroll
;                         for (int r = 0; r < 16; ++r) s0[r] = fast_exp2(s0[r] - mn);
;                     } else {
;                         const float nm = -mn;
; #pragma unroll
;                         for (int r = 0; r < 16; ++r) s0[r] = fast_exp2(__builtin_fmaf(s0[r], c, nm));
.LBB0_508:
	v_sub_f32_e32 v52, v52, v0
	v_cmp_gt_f32_e32 vcc, s30, v52
	s_cmp_lg_u64 vcc, exec
	s_cselect_b64 s[16:17], -1, 0
	s_cmp_eq_u64 vcc, exec
	s_cbranch_scc1 .LBB0_510
	s_cmp_lg_u32 s61, 0
	s_cbranch_scc1 .Lr0_B1_fast
	v_sub_f32_e32 v52, v135, v0
	v_sub_f32_e32 v14, v14, v0
	v_sub_f32_e32 v53, v112, v0
	v_sub_f32_e32 v54, v115, v0
	v_sub_f32_e32 v58, v113, v0
	v_sub_f32_e32 v59, v108, v0
	v_sub_f32_e32 v60, v109, v0
	v_sub_f32_e32 v61, v111, v0
	v_exp_f32_e32 v52, v52
	v_exp_f32_e32 v14, v14
	v_exp_f32_e32 v53, v53
	v_exp_f32_e32 v54, v54
	v_exp_f32_e32 v58, v58
	v_exp_f32_e32 v59, v59
	v_exp_f32_e32 v60, v60
	v_exp_f32_e32 v61, v61
	v_sub_f32_e32 v62, v110, v0
	v_sub_f32_e32 v56, v56, v0
	v_sub_f32_e32 v57, v57, v0
	v_sub_f32_e32 v51, v147, v0
	v_sub_f32_e32 v50, v50, v0
	v_sub_f32_e32 v48, v48, v0
	v_sub_f32_e32 v49, v49, v0
	v_sub_f32_e32 v55, v151, v0
	v_exp_f32_e32 v62, v62
	v_exp_f32_e32 v56, v56
	v_exp_f32_e32 v57, v57
	v_exp_f32_e32 v51, v51
	v_exp_f32_e32 v50, v50
	v_exp_f32_e32 v48, v48
	v_exp_f32_e32 v49, v49
	v_exp_f32_e32 v55, v55

; #define LAS __attribute__((address_space(3)))
; __device__ __forceinline__ float fast_exp2(float x) { return __builtin_amdgcn_exp2f(x); }
; __device__ __forceinline__ float xmax(float a) { auto rr = __builtin_amdgcn_permlane32_swap(__float_as_uint(a), __float_as_uint(a), false, false); return fmaxf(__uint_as_float(rr[0]), __uint_as_float(rr[1])); }
; #define AT_KLOAD(bufbase, hf) do { _Pragma("unroll") for (int j_ = 0; j_ < NK; ++j_) kf[j_] = *(const LAS bf16x8*)((bufbase) + (2 * j_ + hi) * 1024 + (hf) * 512 + r32 * 16); } while (0)
; template <int MODE, int NQ>
; __device__ __forceinline__ void attn_unit(LAS unsigned char* lds, const Params& P, int layer, int b, int h, int qb) {
;     ...
;             AT_VLOAD(cur, hf);
;             if (hf == 0) AT_KLOAD(cur, 1); else if (it + 1 < NT) AT_KLOAD(nxt, 0);
;             __builtin_amdgcn_sched_barrier(0);
;             bf16x8 pw[NC][2]; float rmrel[NC]; bool alive = false;
; #pragma unroll
;             for (int cc = 0; cc < NC; ++cc) {
;                 f32x16& s0 = sc[cc];
;                 float mn;
;                 if (MODE != 0) {
;                     const LAS f32x4* tp4 = (const LAS f32x4*)(tlane + (kt * 64 + hf * 32) * 4);
;                     float rm = -3e38f;
; #pragma unroll
;                     for (int g = 0; g < 4; ++g) { const f32x4 t4 = tp4[2 * g];
; #pragma unroll
;                         for (int i = 0; i < 4; ++i) { s0[4 * g + i] = s0[4 * g + i] * c + t4[i]; rm = fmaxf(rm, s0[4 * g + i]); } }
;                     rm = xmax(rm);
;                     mn = fmaxf(mrun[cc], rm);
;                     rmrel[cc] = rm;
;                 } else {
;                     float rm = -3e38f;
; #pragma unroll
;                     for (int r = 0; r < 16; ++r) rm = fmaxf(rm, s0[r]);
;                     rm = xmax(rm);
;                     mn = fmaxf(mrun[cc], rm * c);
;                 }
;                 if (__any(mn > mrun[cc] + AT_THR)) {
;                     const float al = fast_exp2(mrun[cc] - mn); lrun[cc] *= al;
; #pragma unroll
;                     for (int r = 0; r < 16; ++r) { o[cc][0][r] *= al; o[cc][1][r] *= al; }
;                     mrun[cc] = mn;
;                 }
.LBB0_516:
	s_sub_i32 s10, 0, s20
	v_add_u32_e32 v134, s10, v133
	ds_read_b128 v[112:115], v134 offset:128
	ds_read_b128 v[108:111], v134 offset:160
	ds_read_b128 v[144:147], v134 offset:192
	ds_read_b128 v[148:151], v134 offset:224
	s_waitcnt lgkmcnt(3)
	s_nop 5
	v_fmamk_f32 v135, v48, 0x3e38aa3b, v112
	v_fmamk_f32 v15, v49, 0x3e38aa3b, v113
	v_fmamk_f32 v112, v50, 0x3e38aa3b, v114
	v_fmac_f32_e32 v115, 0x3e38aa3b, v51
	v_max3_f32 v48, v135, s68, v15
	v_max3_f32 v48, v48, v112, v115
	s_waitcnt lgkmcnt(2)
	v_fmamk_f32 v113, v52, 0x3e38aa3b, v108
	v_fmamk_f32 v108, v53, 0x3e38aa3b, v109
	v_max3_f32 v52, v48, v113, v108
	v_fmamk_f32 v109, v54, 0x3e38aa3b, v110
	v_fmac_f32_e32 v111, 0x3e38aa3b, v55
	v_max3_f32 v114, v52, v109, v111
	s_waitcnt lgkmcnt(1)
	v_fmamk_f32 v110, v56, 0x3e38aa3b, v144
	v_fmamk_f32 v56, v57, 0x3e38aa3b, v145
	v_max3_f32 v48, v114, v110, v56
	v_fmamk_f32 v57, v58, 0x3e38aa3b, v146
	v_fmac_f32_e32 v147, 0x3e38aa3b, v59
	v_max3_f32 v49, v48, v57, v147
	s_waitcnt lgkmcnt(0)
	v_fmamk_f32 v50, v60, 0x3e38aa3b, v148
	v_fmamk_f32 v48, v61, 0x3e38aa3b, v149
	v_max3_f32 v52, v49, v50, v48
	v_fmamk_f32 v49, v62, 0x3e38aa3b, v150
	v_fmac_f32_e32 v151, 0x3e38aa3b, v63
	v_max3_f32 v52, v52, v49, v151
	v_mov_b32_e32 v53, v52
	s_nop 1
	v_permlane32_swap_b32_e32 v52, v53
	v_max_f32_e32 v52, v52, v53
	v_max_f32_e32 v134, v0, v52
	v_add_f32_e32 v53, 0x41000000, v0
	v_cmp_gt_f32_e32 vcc, v134, v53
	s_cbranch_vccz .LBB0_518
	v_sub_f32_e32 v0, v0, v134
	s_mov_b32 s61, 0
	v_exp_f32_e32 v0, v0
	s_nop 0
	v_pk_mul_f32 v[46:47], v[46:47], v[0:1] op_sel_hi:[1,0]
	v_pk_mul_f32 v[44:45], v[44:45], v[0:1] op_sel_hi:[1,0]
	v_pk_mul_f32 v[42:43], v[42:43], v[0:1] op_sel_hi:[1,0]
	v_pk_mul_f32 v[40:41], v[40:41], v[0:1] op_sel_hi:[1,0]
	v_pk_mul_f32 v[38:39], v[38:39], v[0:1] op_sel_hi:[1,0]
	v_pk_mul_f32 v[36:37], v[36:37], v[0:1] op_sel_hi:[1,0]
	v_pk_mul_f32 v[34:35], v[34:35], v[0:1] op_sel_hi:[1,0]
	v_pk_mul_f32 v[32:33], v[32:33], v[0:1] op_sel_hi:[1,0]
	v_pk_mul_f32 v[30:31], v[30:31], v[0:1] op_sel_hi:[1,0]
	v_pk_mul_f32 v[28:29], v[28:29], v[0:1] op_sel_hi:[1,0]
	v_pk_mul_f32 v[26:27], v[26:27], v[0:1] op_sel_hi:[1,0]
	v_pk_mul_f32 v[24:25], v[24:25], v[0:1] op_sel_hi:[1,0]
	v_pk_mul_f32 v[22:23], v[22:23], v[0:1] op_sel_hi:[1,0]
	v_pk_mul_f32 v[20:21], v[20:21], v[0:1] op_sel_hi:[1,0]
	v_pk_mul_f32 v[18:19], v[18:19], v[0:1] op_sel_hi:[1,0]
	v_pk_mul_f32 v[16:17], v[16:17], v[0:1] op_sel_hi:[1,0]
	v_mul_f32_e32 v132, v132, v0
	s_branch .LBB0_519

; __device__ __forceinline__ float fast_exp2(float x) { return __builtin_amdgcn_exp2f(x); }
; template <int MODE, int NQ>
; __device__ __forceinline__ void attn_unit(LAS unsigned char* lds, const Params& P, int layer, int b, int h, int qb) {
;     ...
;                 mn = mrun[cc];
;                 if (MODE != 0) rmrel[cc] -= mn;
;                 const bool dead = (MODE != 0) && __all(rmrel[cc] < -136.f);
;                 if (dead) { pw[cc][0] = zero8; pw[cc][1] = zero8; }
;                 else {
;                     alive = true;
;                     if (MODE != 0) {
; #pragma unroll
;                         for (int r = 0; r < 16; ++r) s0[r] = fast_exp2(s0[r] - mn);
;                     } else {
;                         const float nm = -mn;
; #pragma unroll
;                         for (int r = 0; r < 16; ++r) s0[r] = fast_exp2(__builtin_fmaf(s0[r], c, nm));
.LBB0_519:
	v_sub_f32_e32 v0, v52, v134
	v_cmp_gt_f32_e32 vcc, s30, v0
	s_cmp_lg_u64 vcc, exec
	s_cselect_b64 s[10:11], -1, 0
	s_cmp_eq_u64 vcc, exec
	s_cbranch_scc1 .LBB0_521
	s_cmp_lg_u32 s61, 0
	s_cbranch_scc1 .Lr0_B2_fast
	v_sub_f32_e32 v0, v135, v134
	v_sub_f32_e32 v15, v15, v134
	v_sub_f32_e32 v52, v112, v134
	v_sub_f32_e32 v53, v115, v134
	v_sub_f32_e32 v54, v113, v134
	v_sub_f32_e32 v58, v108, v134
	v_sub_f32_e32 v59, v109, v134
	v_sub_f32_e32 v60, v111, v134
	v_exp_f32_e32 v0, v0
	v_exp_f32_e32 v15, v15
	v_exp_f32_e32 v52, v52
	v_exp_f32_e32 v53, v53
	v_exp_f32_e32 v54, v54
	v_exp_f32_e32 v58, v58
	v_exp_f32_e32 v59, v59
	v_exp_f32_e32 v60, v60
	v_sub_f32_e32 v61, v110, v134
	v_sub_f32_e32 v56, v56, v134
	v_sub_f32_e32 v57, v57, v134
	v_sub_f32_e32 v51, v147, v134
	v_sub_f32_e32 v50, v50, v134
	v_sub_f32_e32 v48, v48, v134
	v_sub_f32_e32 v49, v49, v134
	v_sub_f32_e32 v55, v151, v134
	v_exp_f32_e32 v61, v61
	v_exp_f32_e32 v56, v56
	v_exp_f32_e32 v57, v57
	v_exp_f32_e32 v51, v51
	v_exp_f32_e32 v50, v50
	v_exp_f32_e32 v48, v48
	v_exp_f32_e32 v49, v49
	v_exp_f32_e32 v55, v55

; __device__ __forceinline__ float fast_exp2(float x) { return __builtin_amdgcn_exp2f(x); }
; template <int MODE, int NQ>
; __device__ __forceinline__ void attn_unit(LAS unsigned char* lds, const Params& P, int layer, int b, int h, int qb) {
;     ...
;                     if (MODE != 0) {
; #pragma unroll
;                         for (int r = 0; r < 16; ++r) s0[r] = fast_exp2(s0[r] - mn);
.Lr0_B1_fast:
	v_exp_f32_e32 v52, v135
	v_exp_f32_e32 v14, v14
	v_exp_f32_e32 v53, v112
	v_exp_f32_e32 v54, v115
	v_exp_f32_e32 v58, v113
	v_exp_f32_e32 v59, v108
	v_exp_f32_e32 v60, v109
	v_exp_f32_e32 v61, v111
	v_exp_f32_e32 v62, v110
	v_exp_f32_e32 v56, v56
	v_exp_f32_e32 v57, v57
	v_exp_f32_e32 v51, v147
	v_exp_f32_e32 v50, v50
	v_exp_f32_e32 v48, v48
	v_exp_f32_e32 v49, v49
	v_exp_f32_e32 v55, v151
	s_branch .Lr0_B1_join
.Lr0_B2_fast:
	v_exp_f32_e32 v0, v135
	v_exp_f32_e32 v15, v15
	v_exp_f32_e32 v52, v112
	v_exp_f32_e32 v53, v115
	v_exp_f32_e32 v54, v113
	v_exp_f32_e32 v58, v108
	v_exp_f32_e32 v59, v109
	v_exp_f32_e32 v60, v111
	v_exp_f32_e32 v61, v110
	v_exp_f32_e32 v56, v56
	v_exp_f32_e32 v57, v57
	v_exp_f32_e32 v51, v147
	v_exp_f32_e32 v50, v50
	v_exp_f32_e32 v48, v48
	v_exp_f32_e32 v49, v49
	v_exp_f32_e32 v55, v151
	s_branch .Lr0_B2_join
